# GLA pre-pass items: bias loads issued before the next-item prefetch, counted waits instead of full drains, loads drained once before the item's stores
# speedup vs baseline: 1.0063x; 1.0063x over previous
; #define LAS __attribute__((address_space(3)))
; __device__ __forceinline__ float bflo(unsigned w) { return __uint_as_float(w << 16); }
; __device__ __forceinline__ float bfhi(unsigned w) { return __uint_as_float(w & 0xffff0000u); }
; __device__ __forceinline__ void gla_pre_items(LAS unsigned char* lds, const bf16* PROJ, const float* A2, const float* ba, unsigned char* GPRE, int first, int stride, int nitems) {
;     ...
;     PRE_LOAD(first);
; #pragma unroll 1
;     for (int item = first; item < nitems; item += stride) {
;     const int bh = item >> 5, ch = item & 31, b = bh >> 2, h = bh & 3;
;     unsigned char* gp = GPRE + (size_t)item * GP_ITEM;
;     if (tid < 128) { const int t = tid >> 1, hq = tid & 1; const v4u w = rlr;
;         *(LAS f32x4*)(LRs + t * 16 + hq * 8) = (f32x4){bflo(w.x), bfhi(w.x), bflo(w.y), bfhi(w.y)}; *(LAS f32x4*)(LRs + t * 16 + hq * 8 + 4) = (f32x4){bflo(w.z), bfhi(w.z), bflo(w.w), bfhi(w.w)}; }
; #pragma unroll
;     for (int i = 0; i < 3; ++i) { const int idx = tid + 512 * i, t = idx / 24, cq = idx - t * 24;
;         if (cq < 12) *(LAS v4u*)(QTs + t * 104 + cq * 8) = rqk[i]; else *(LAS v4u*)(KTs + t * 104 + (cq - 12) * 8) = rqk[i];
;         A2s[idx] = ra2[i];
;         const v4u w = rv[i]; LAS bf16* vp = VTs + (cq * 8) * 72 + t;
;         vp[0 * 72] = (bf16)(w.x & 0xffffu); vp[1 * 72] = (bf16)(w.x >> 16); vp[2 * 72] = (bf16)(w.y & 0xffffu); vp[3 * 72] = (bf16)(w.y >> 16);
;         vp[4 * 72] = (bf16)(w.z & 0xffffu); vp[5 * 72] = (bf16)(w.z >> 16); vp[6 * 72] = (bf16)(w.w & 0xffffu); vp[7 * 72] = (bf16)(w.w >> 16); }
;     if (item + stride < nitems) PRE_LOAD(item + stride);
.LBB0_658:
	s_or_b64 exec, exec, s[0:1]
	v_mul_hi_i32 v2, v38, s96
	v_ashrrev_i32_e32 v8, 2, v2
	v_lshrrev_b32_e32 v16, 31, v2
	s_waitcnt vmcnt(5)
	v_add_u32_e32 v44, v8, v16
	v_readlane_b32 s8, v254, 11
	v_ashrrev_i32_e32 v45, 31, v44
	v_readlane_b32 s9, v254, 12
	s_movk_i32 s12, 0xffe8
	v_mov_b64_e32 v[24:25], s[88:89]
	v_lshl_add_u64 v[8:9], v[44:45], 0, s[8:9]
	v_mad_u64_u32 v[36:37], s[0:1], v44, s12, v[38:39]
	v_mad_u64_u32 v[10:11], s[0:1], v8, s77, v[24:25]
	v_readlane_b32 s0, v254, 14
	v_cmp_gt_i32_e64 s[4:5], 12, v36
	s_waitcnt vmcnt(4)
	v_lshlrev_b32_e32 v46, 3, v36
	v_mov_b32_e32 v30, s0
	v_readlane_b32 s0, v254, 16
	v_readlane_b32 s14, v255, 20
	v_readlane_b32 s15, v255, 21
	v_mov_b32_e32 v31, s0
	v_cndmask_b32_e64 v8, v30, v31, s[4:5]
	v_add_u32_e32 v8, v8, v46
	v_lshrrev_b32_e32 v2, 4, v2
	v_mad_i32_i24 v11, v9, s77, v11
	v_ashrrev_i32_e32 v9, 31, v8
	s_mov_b32 s15, s35
	v_add_u32_e32 v2, v2, v16
	s_movk_i32 s13, 0x120
	v_lshl_add_u64 v[8:9], v[8:9], 1, v[10:11]
	v_lshl_add_u64 v[10:11], v[10:11], 0, s[14:15]
	v_ashrrev_i32_e32 v47, 31, v46
	v_mul_lo_u32 v33, v2, s13
	v_readlane_b32 s10, v254, 15
	v_lshl_add_u64 v[10:11], v[46:47], 1, v[10:11]
	s_movk_i32 s11, 0x1000
	v_add3_u32 v16, v38, s10, v33
	v_add_co_u32_e32 v12, vcc, s11, v10
	v_ashrrev_i32_e32 v17, 31, v16
	v_add_u32_e32 v2, 0x200, v38
	v_addc_co_u32_e32 v13, vcc, 0, v11, vcc
	v_lshl_add_u64 v[16:17], v[16:17], 2, s[92:93]
	v_mul_hi_i32 v26, v2, s96
	global_load_dwordx4 v[8:11], v[8:9], off
	s_nop 0
	global_load_dwordx4 v[12:15], v[12:13], off offset:1536
	v_lshrrev_b32_e32 v27, 31, v26
	global_load_dword v61, v[16:17], off
	v_ashrrev_i32_e32 v16, 2, v26
	v_lshrrev_b32_e32 v26, 4, v26
	v_add_u32_e32 v48, v16, v27
	v_add_u32_e32 v26, v26, v27
	s_waitcnt vmcnt(3)
	v_mad_u64_u32 v[62:63], s[0:1], v48, s12, v[2:3]
	v_mad_u64_u32 v[52:53], s[0:1], v26, s13, v[2:3]
	v_add_u32_e32 v2, 0x400, v38
	v_mul_hi_i32 v35, v2, s96
	v_ashrrev_i32_e32 v28, 2, v35
	v_lshrrev_b32_e32 v37, 31, v35
	v_ashrrev_i32_e32 v49, 31, v48
	v_add_u32_e32 v54, v28, v37
	v_lshl_add_u64 v[16:17], v[48:49], 0, s[8:9]
	v_cmp_gt_i32_e64 s[6:7], 12, v62
	v_ashrrev_i32_e32 v55, 31, v54
	v_mad_u64_u32 v[18:19], s[0:1], v16, s77, v[24:25]
	v_cndmask_b32_e64 v16, v30, v31, s[6:7]
	v_lshlrev_b32_e32 v50, 3, v62
	v_lshl_add_u64 v[28:29], v[54:55], 0, s[8:9]
	v_add_u32_e32 v16, v16, v50
	v_mad_u64_u32 v[24:25], s[0:1], v28, s77, v[24:25]
	v_mad_i32_i24 v19, v17, s77, v19
	v_ashrrev_i32_e32 v17, 31, v16
	v_mad_i32_i24 v25, v29, s77, v25
	v_lshrrev_b32_e32 v29, 4, v35
	v_lshl_add_u64 v[16:17], v[16:17], 1, v[18:19]
	v_lshl_add_u64 v[18:19], v[18:19], 0, s[14:15]
	v_ashrrev_i32_e32 v51, 31, v50
	v_mad_u64_u32 v[78:79], s[0:1], v54, s12, v[2:3]
	v_add_u32_e32 v29, v29, v37
	v_lshl_add_u64 v[18:19], v[50:51], 1, v[18:19]
	v_add_u32_e32 v26, s10, v52
	v_cmp_gt_i32_e64 s[8:9], 12, v78
	v_mad_u64_u32 v[58:59], s[0:1], v29, s13, v[2:3]
	v_add_co_u32_e32 v20, vcc, s11, v18
	v_ashrrev_i32_e32 v27, 31, v26
	v_cndmask_b32_e64 v28, v30, v31, s[8:9]
	v_add_u32_e32 v30, s10, v58
	v_addc_co_u32_e32 v21, vcc, 0, v19, vcc
	v_lshl_add_u64 v[26:27], v[26:27], 2, s[92:93]
	v_lshlrev_b32_e32 v56, 3, v78
	v_ashrrev_i32_e32 v31, 31, v30
	global_load_dwordx4 v[16:19], v[16:17], off
	s_nop 0
	global_load_dwordx4 v[20:23], v[20:21], off offset:1536
	v_ashrrev_i32_e32 v57, 31, v56
	v_lshl_add_u64 v[30:31], v[30:31], 2, s[92:93]
	global_load_dword v83, v[26:27], off
	global_load_dword v84, v[30:31], off
	v_lshl_add_u64 v[26:27], v[24:25], 0, s[14:15]
	v_add_u32_e32 v28, v28, v56
	v_lshl_add_u64 v[26:27], v[56:57], 1, v[26:27]
	v_add_co_u32_e32 v26, vcc, s11, v26
	v_ashrrev_i32_e32 v29, 31, v28
	s_nop 0
	v_addc_co_u32_e32 v27, vcc, 0, v27, vcc
	v_lshl_add_u64 v[24:25], v[28:29], 1, v[24:25]
	global_load_dwordx4 v[28:31], v[26:27], off offset:1536
	s_nop 0
	global_load_dwordx4 v[24:27], v[24:25], off
	s_mov_b32 s0, s14
	v_and_b32_e32 v2, 0x3ffffff0, v34
	v_writelane_b32 v255, s0, 20
	v_lshlrev_b32_e32 v2, 2, v2
	v_lshlrev_b32_e32 v32, 2, v32
	v_and_b32_e32 v64, 15, v38
	v_writelane_b32 v255, s1, 21
	v_add3_u32 v53, 0, v2, v32
	v_lshl_add_u32 v32, v64, 6, 0
	s_movk_i32 s0, 0xffc4
	v_mad_i32_i24 v67, v64, s0, v32
	s_movk_i32 s0, 0x60
	v_bfe_u32 v2, v38, 4, 2
	v_cmp_gt_i32_e64 s[16:17], s0, v38
	s_movk_i32 s0, 0x600
	v_lshlrev_b32_e32 v65, 2, v2
	v_cmp_gt_i32_e64 s[22:23], s0, v38
	s_movk_i32 s0, 0xd0
	v_add_u32_e32 v66, v32, v65
	v_mul_lo_u32 v32, v44, s0
	s_movk_i32 s1, 0x480
	v_add_u32_e32 v69, 0, v32
	v_mul_lo_u32 v32, v36, s1
	v_lshlrev_b32_e32 v34, 1, v44
	v_add3_u32 v71, s64, v32, v34
	v_mul_lo_u32 v32, v48, s0
	v_add_u32_e32 v72, 0, v32
	v_mul_lo_u32 v32, v62, s1
	v_lshlrev_b32_e32 v34, 1, v48
	v_add3_u32 v74, s64, v32, v34
	v_mul_lo_u32 v32, v54, s0
	s_movk_i32 s0, 0x180
	v_lshl_add_u32 v60, v2, 4, 0
	v_mad_u32_u24 v79, v2, s0, v67
	v_mul_lo_u32 v2, v38, s66
	v_readlane_b32 s0, v255, 22
	v_add_u32_e32 v75, 0, v32
	v_mul_lo_u32 v32, v78, s1
	v_lshlrev_b32_e32 v34, 1, v54
	v_add_u32_e32 v80, s0, v2
	v_readlane_b32 s0, v255, 23
	v_cmp_lt_i32_e64 s[10:11], 11, v36
	v_cmp_lt_i32_e64 s[12:13], 11, v62
	v_cmp_lt_i32_e64 s[14:15], 11, v78
	v_ashrrev_i32_e32 v59, 6, v38
	v_lshl_add_u32 v68, v38, 2, 0
	v_cmp_gt_i32_e64 s[18:19], s56, v38
	v_ashrrev_i32_e32 v39, 31, v38
	v_cmp_gt_i32_e64 s[20:21], s76, v38
	v_lshlrev_b32_e32 v70, 4, v36
	v_lshlrev_b32_e32 v73, 4, v62
	s_movk_i32 s50, 0xd0
	v_lshlrev_b32_e32 v76, 4, v78
	v_add3_u32 v77, s64, v32, v34
	v_add_u32_e32 v78, v33, v38
	v_lshl_add_u32 v81, v38, 1, s0
	v_lshlrev_b32_e32 v82, 4, v38
	v_readlane_b32 s40, v254, 13
	s_waitcnt vmcnt(0)
	s_branch .LBB0_660

; #define LAS __attribute__((address_space(3)))
; __device__ __forceinline__ float bflo(unsigned w) { return __uint_as_float(w << 16); }
; __device__ __forceinline__ float bfhi(unsigned w) { return __uint_as_float(w & 0xffff0000u); }
; __device__ __forceinline__ void gla_pre_items(LAS unsigned char* lds, const bf16* PROJ, const float* A2, const float* ba, unsigned char* GPRE, int first, int stride, int nitems) {
;     ...
;     PRE_LOAD(first);
; #pragma unroll 1
;     for (int item = first; item < nitems; item += stride) {
;     const int bh = item >> 5, ch = item & 31, b = bh >> 2, h = bh & 3;
;     unsigned char* gp = GPRE + (size_t)item * GP_ITEM;
;     if (tid < 128) { const int t = tid >> 1, hq = tid & 1; const v4u w = rlr;
;         *(LAS f32x4*)(LRs + t * 16 + hq * 8) = (f32x4){bflo(w.x), bfhi(w.x), bflo(w.y), bfhi(w.y)}; *(LAS f32x4*)(LRs + t * 16 + hq * 8 + 4) = (f32x4){bflo(w.z), bfhi(w.z), bflo(w.w), bfhi(w.w)}; }
; #pragma unroll
;     for (int i = 0; i < 3; ++i) { const int idx = tid + 512 * i, t = idx / 24, cq = idx - t * 24;
;         if (cq < 12) *(LAS v4u*)(QTs + t * 104 + cq * 8) = rqk[i]; else *(LAS v4u*)(KTs + t * 104 + (cq - 12) * 8) = rqk[i];
;         A2s[idx] = ra2[i];
;         const v4u w = rv[i]; LAS bf16* vp = VTs + (cq * 8) * 72 + t;
;         vp[0 * 72] = (bf16)(w.x & 0xffffu); vp[1 * 72] = (bf16)(w.x >> 16); vp[2 * 72] = (bf16)(w.y & 0xffffu); vp[3 * 72] = (bf16)(w.y >> 16);
;         vp[4 * 72] = (bf16)(w.z & 0xffffu); vp[5 * 72] = (bf16)(w.z >> 16); vp[6 * 72] = (bf16)(w.w & 0xffffu); vp[7 * 72] = (bf16)(w.w >> 16); }
;     if (item + stride < nitems) PRE_LOAD(item + stride);
;     __syncthreads();
;     {
;         const int wv = __builtin_amdgcn_readfirstlane(tid >> 6), ln = tid & 63, g = ln >> 4, c = ln & 15;
; #pragma unroll
;         for (int rep3 = 0; rep3 < 3; ++rep3) { const int id = wv + 8 * rep3, tt = id / 6, dd = id - tt * 6;
;             f32x4 z = (f32x4){0.f, 0.f, 0.f, 0.f};
; #pragma unroll
;             for (int ks = 0; ks < 4; ++ks) z = __builtin_amdgcn_mfma_f32_16x16x4f32(LRs[(16 * tt + c) * 16 + 4 * ks + g], A2s[(4 * ks + g) * 96 + 16 * dd + c], z, 0, 0, 0);
;             const float bb = ba[h * 96 + 16 * dd + c];
.LBB0_663:
	v_add_u32_e32 v2, v69, v70
	ds_write_b128 v2, v[8:11] offset:34816
.LBB0_664:
	s_or_b64 exec, exec, s[0:1]
	ds_write_b32 v68, v61 offset:4096
	ds_write_b16 v71, v12
	ds_write_b16_d16_hi v71, v12 offset:144
	ds_write_b16 v71, v13 offset:288
	ds_write_b16_d16_hi v71, v13 offset:432
	ds_write_b16 v71, v14 offset:576
	ds_write_b16_d16_hi v71, v14 offset:720
	ds_write_b16 v71, v15 offset:864
	ds_write_b16_d16_hi v71, v15 offset:1008
	s_and_saveexec_b64 s[0:1], s[12:13]
	s_xor_b64 s[0:1], exec, s[0:1]
	s_cbranch_execz .LBB0_666
	v_add_u32_e32 v2, v72, v73
	ds_write_b128 v2, v[16:19] offset:47936
.LBB0_666:
	s_andn2_saveexec_b64 s[0:1], s[0:1]
	s_cbranch_execz .LBB0_668
	v_add_u32_e32 v2, v72, v73
	ds_write_b128 v2, v[16:19] offset:34816
.LBB0_668:
	s_or_b64 exec, exec, s[0:1]
	ds_write_b32 v68, v83 offset:6144
	ds_write_b16 v74, v20
	ds_write_b16_d16_hi v74, v20 offset:144
	ds_write_b16 v74, v21 offset:288
	ds_write_b16_d16_hi v74, v21 offset:432
	ds_write_b16 v74, v22 offset:576
	ds_write_b16_d16_hi v74, v22 offset:720
	ds_write_b16 v74, v23 offset:864
	ds_write_b16_d16_hi v74, v23 offset:1008
	s_and_saveexec_b64 s[0:1], s[14:15]
	s_xor_b64 s[0:1], exec, s[0:1]
	s_cbranch_execz .LBB0_670
	v_add_u32_e32 v2, v75, v76
	ds_write_b128 v2, v[24:27] offset:47936
.LBB0_670:
	s_andn2_saveexec_b64 s[0:1], s[0:1]
	s_cbranch_execz .LBB0_672
	v_add_u32_e32 v2, v75, v76
	ds_write_b128 v2, v[24:27] offset:34816
.LBB0_672:
	s_or_b64 exec, exec, s[0:1]
	s_add_i32 s26, s40, s69
	s_cmpk_gt_i32 s26, 0x1ff
	s_cselect_b64 s[86:87], -1, 0
	s_and_b64 vcc, exec, s[86:87]
	ds_write_b32 v68, v84 offset:8192
	ds_write_b16 v77, v28
	ds_write_b16_d16_hi v77, v28 offset:144
	ds_write_b16 v77, v29 offset:288
	ds_write_b16_d16_hi v77, v29 offset:432
	ds_write_b16 v77, v30 offset:576
	ds_write_b16_d16_hi v77, v30 offset:720
	ds_write_b16 v77, v31 offset:864
	ds_write_b16_d16_hi v77, v31 offset:1008
	v_readfirstlane_b32 s38, v59
	s_bfe_u32 s32, s40, 0x20005
	s_mulk_i32 s32, 0x60
	v_or_b32_e32 v184, s32, v64
	s_mul_hi_i32 s44, s38, 0x2aaaaaab
	s_lshr_b32 s46, s44, 31
	s_add_i32 s44, s44, s46
	s_mul_i32 s46, s44, -6
	s_add_i32 s46, s46, s38
	v_lshl_add_u32 v186, s46, 4, v184
	v_ashrrev_i32_e32 v187, 31, v186
	v_lshl_add_u64 v[186:187], v[186:187], 2, s[70:71]
	global_load_dword v188, v[186:187], off
	s_add_i32 s38, s38, 8
	s_mul_hi_i32 s44, s38, 0x2aaaaaab
	s_lshr_b32 s46, s44, 31
	s_add_i32 s44, s44, s46
	s_mul_i32 s46, s44, -6
	s_add_i32 s46, s46, s38
	v_lshl_add_u32 v186, s46, 4, v184
	v_ashrrev_i32_e32 v187, 31, v186
	v_lshl_add_u64 v[186:187], v[186:187], 2, s[70:71]
	global_load_dword v189, v[186:187], off
	s_add_i32 s38, s38, 8
	s_mul_hi_i32 s44, s38, 0x2aaaaaab
	s_lshr_b32 s46, s44, 31
	s_add_i32 s44, s44, s46
	s_mul_i32 s46, s44, -6
	s_add_i32 s46, s46, s38
	v_lshl_add_u32 v186, s46, 4, v184
	v_ashrrev_i32_e32 v187, 31, v186
	v_lshl_add_u64 v[186:187], v[186:187], 2, s[70:71]
	global_load_dword v190, v[186:187], off
	s_cbranch_vccnz .LBB0_676
	s_lshl_b32 s0, s26, 4
	s_lshl_b32 s1, s26, 6
	s_and_b32 s0, s0, 0xfffff800
	s_and_b32 s1, s1, 0x7c0
	s_or_b32 s0, s0, s1
	s_ashr_i32 s1, s0, 31
	s_and_saveexec_b64 s[24:25], s[2:3]
	s_cbranch_execz .LBB0_675
	v_lshl_add_u64 v[4:5], v[40:41], 0, s[0:1]
	v_mov_b64_e32 v[6:7], s[88:89]
	v_mad_u64_u32 v[6:7], s[48:49], v4, s77, v[6:7]
	v_mov_b32_e32 v2, v7
	v_mad_u64_u32 v[4:5], s[48:49], v5, s77, v[2:3]
	v_mov_b32_e32 v7, v4
	v_lshl_add_u64 v[4:5], v[42:43], 1, v[6:7]
	v_add_co_u32_e32 v4, vcc, 0x2000, v4
	s_nop 1
	v_addc_co_u32_e32 v5, vcc, 0, v5, vcc
	global_load_dwordx4 v[4:7], v[4:5], off offset:512
.LBB0_675:
	s_or_b64 exec, exec, s[24:25]
	s_bfe_u32 s41, s26, 0x20005
	s_mul_i32 s45, s41, 0x60
	s_add_i32 s42, s45, 0x920
	s_or_b32 s48, s45, 0x800
	v_lshl_add_u64 v[8:9], s[0:1], 0, v[44:45]
	v_mov_b64_e32 v[24:25], s[88:89]
	v_mov_b32_e32 v2, s42
	v_mov_b32_e32 v28, s48
	v_mad_u64_u32 v[10:11], s[24:25], v8, s77, v[24:25]
	v_cndmask_b32_e64 v8, v2, v28, s[4:5]
	v_add_u32_e32 v8, v8, v46
	v_mad_i32_i24 v11, v9, s77, v11
	v_ashrrev_i32_e32 v9, 31, v8
	s_mul_i32 s34, s41, 0x180
	v_lshl_add_u64 v[8:9], v[8:9], 1, v[10:11]
	v_lshl_add_u64 v[10:11], v[10:11], 0, s[34:35]
	v_lshl_add_u64 v[10:11], v[46:47], 1, v[10:11]
	s_movk_i32 s27, 0x1000
	v_add_u32_e32 v16, s45, v78
	v_add_co_u32_e32 v12, vcc, s27, v10
	v_ashrrev_i32_e32 v17, 31, v16
	s_nop 0
	v_addc_co_u32_e32 v13, vcc, 0, v11, vcc
	v_lshl_add_u64 v[16:17], v[16:17], 2, s[92:93]
	global_load_dwordx4 v[8:11], v[8:9], off
	s_nop 0
	global_load_dwordx4 v[12:15], v[12:13], off offset:1536
	v_add_u32_e32 v26, s45, v52
	global_load_dword v61, v[16:17], off
	v_lshl_add_u64 v[16:17], s[0:1], 0, v[48:49]
	v_mad_u64_u32 v[18:19], s[24:25], v16, s77, v[24:25]
	v_cndmask_b32_e64 v16, v2, v28, s[6:7]
	v_add_u32_e32 v16, v16, v50
	v_mad_i32_i24 v19, v17, s77, v19
	v_ashrrev_i32_e32 v17, 31, v16
	v_lshl_add_u64 v[16:17], v[16:17], 1, v[18:19]
	v_lshl_add_u64 v[18:19], v[18:19], 0, s[34:35]
	v_lshl_add_u64 v[18:19], v[50:51], 1, v[18:19]
	v_add_co_u32_e32 v20, vcc, s27, v18
	v_ashrrev_i32_e32 v27, 31, v26
	s_nop 0
	v_addc_co_u32_e32 v21, vcc, 0, v19, vcc
	v_lshl_add_u64 v[26:27], v[26:27], 2, s[92:93]
	global_load_dwordx4 v[16:19], v[16:17], off
	s_nop 0
	global_load_dwordx4 v[20:23], v[20:21], off offset:1536
	v_cndmask_b32_e64 v2, v2, v28, s[8:9]
	global_load_dword v83, v[26:27], off
	v_lshl_add_u64 v[26:27], s[0:1], 0, v[54:55]
	v_mad_u64_u32 v[24:25], s[0:1], v26, s77, v[24:25]
	v_add_u32_e32 v26, v2, v56
	v_mad_i32_i24 v25, v27, s77, v25
	v_ashrrev_i32_e32 v27, 31, v26
	v_lshl_add_u64 v[26:27], v[26:27], 1, v[24:25]
	v_lshl_add_u64 v[24:25], v[24:25], 0, s[34:35]
	v_lshl_add_u64 v[24:25], v[56:57], 1, v[24:25]
	v_add_u32_e32 v32, s45, v58
	v_add_co_u32_e32 v28, vcc, s27, v24
	v_ashrrev_i32_e32 v33, 31, v32
	s_nop 0
	v_addc_co_u32_e32 v29, vcc, 0, v25, vcc
	v_lshl_add_u64 v[32:33], v[32:33], 2, s[92:93]
	global_load_dwordx4 v[24:27], v[26:27], off
	s_nop 0
	global_load_dwordx4 v[28:31], v[28:29], off offset:1536
	s_nop 0
	global_load_dword v84, v[32:33], off
; __device__ __forceinline__ void gla_pre_items(LAS unsigned char* lds, const bf16* PROJ, const float* A2, const float* ba, unsigned char* GPRE, int first, int stride, int nitems) {
;     ...
;     __syncthreads();
;     {
;         const int wv = __builtin_amdgcn_readfirstlane(tid >> 6), ln = tid & 63, g = ln >> 4, c = ln & 15;
; #pragma unroll
;         for (int rep3 = 0; rep3 < 3; ++rep3) { const int id = wv + 8 * rep3, tt = id / 6, dd = id - tt * 6;
;             f32x4 z = (f32x4){0.f, 0.f, 0.f, 0.f};
; #pragma unroll
;             for (int ks = 0; ks < 4; ++ks) z = __builtin_amdgcn_mfma_f32_16x16x4f32(LRs[(16 * tt + c) * 16 + 4 * ks + g], A2s[(4 * ks + g) * 96 + 16 * dd + c], z, 0, 0, 0);
;             const float bb = ba[h * 96 + 16 * dd + c];
; #pragma unroll
;             for (int r = 0; r < 4; ++r) { const float zz = z[r] + bb; const float ls = fminf(zz, 0.f) - __logf(1.0f + __expf(-fabsf(zz)));
;                 Bs[(16 * tt + 4 * g + r) * 96 + 16 * dd + c] = ls * (1.0f / 16.0f); } }
.LBB0_676:
	s_bfe_u32 s0, s40, 0x20005
	v_readfirstlane_b32 s24, v59
	s_mulk_i32 s0, 0x60
	v_or_b32_e32 v2, s0, v64
	s_mul_hi_i32 s0, s24, 0x2aaaaaab
	s_lshr_b32 s1, s0, 31
	s_add_i32 s0, s0, s1
	s_mul_i32 s1, s0, -6
	s_add_i32 s1, s1, s24
	s_lshl_b32 s25, s1, 6
	v_add_u32_e32 v85, s25, v79
	s_waitcnt lgkmcnt(0)
	s_barrier
	v_lshl_add_u32 v32, s0, 10, v66
	ds_read2st64_b32 v[36:37], v85 offset0:16 offset1:22
	ds_read2_b32 v[62:63], v32 offset1:4
	ds_read2_b32 v[86:87], v32 offset0:8 offset1:12
	s_waitcnt lgkmcnt(1)
	v_mfma_f32_16x16x4_f32 v[32:35], v62, v36, 0
	s_mov_b32 s27, 0xbfb8aa3b
	s_mov_b32 s42, 0x800000
	s_mov_b32 s45, 0x3f317217
	s_mov_b32 s48, 0x7f800000
	s_movk_i32 s34, 0x180
	v_mfma_f32_16x16x4_f32 v[32:35], v63, v37, v[32:35]
	ds_read2st64_b32 v[36:37], v85 offset0:28 offset1:34
	s_waitcnt lgkmcnt(0)
	v_mfma_f32_16x16x4_f32 v[32:35], v86, v36, v[32:35]
	v_lshl_add_u32 v36, s1, 4, v2
	v_mfma_f32_16x16x4_f32 v[32:35], v87, v37, v[32:35]
	v_ashrrev_i32_e32 v37, 31, v36
	v_lshl_add_u64 v[36:37], v[36:37], 2, s[70:71]
	v_lshl_or_b32 v37, s0, 4, v65
	v_mul_lo_u32 v37, v37, s34
	v_add3_u32 v37, v67, s25, v37
	s_cmp_eq_u64 s[86:87], 0
	s_cbranch_scc1 .Lgp_pf_a
	s_waitcnt vmcnt(0)
.Lgp_pf_a:
	s_waitcnt vmcnt(10)
	v_mov_b32_e32 v36, v188
	s_nop 2
	v_add_f32_e32 v32, v36, v32
	v_min_f32_e32 v62, 0, v32
	v_mul_f32_e64 v32, |v32|, s27
	v_exp_f32_e32 v32, v32
	v_add_f32_e32 v33, v36, v33
	v_add_f32_e32 v32, 1.0, v32
	v_cmp_gt_f32_e32 vcc, s42, v32
	s_nop 1
	v_cndmask_b32_e64 v63, 0, 32, vcc
	v_ldexp_f32 v32, v32, v63
	v_log_f32_e32 v32, v32
	s_nop 0
	v_mul_f32_e32 v63, 0x3f317217, v32
	v_fma_f32 v63, v32, s45, -v63
	v_fmac_f32_e32 v63, 0x3377d1cf, v32
	v_fmac_f32_e32 v63, 0x3f317217, v32
	v_cmp_lt_f32_e64 s[0:1], |v32|, s48
	s_nop 1
	v_cndmask_b32_e64 v32, v32, v63, s[0:1]
	v_cndmask_b32_e32 v63, 0, v222, vcc
	v_sub_f32_e32 v32, v32, v63
	v_sub_f32_e32 v32, v62, v32
	v_min_f32_e32 v62, 0, v33
	v_mul_f32_e64 v33, |v33|, s27
	v_exp_f32_e32 v33, v33
	v_mul_f32_e32 v32, 0x3d800000, v32
	v_add_f32_e32 v33, 1.0, v33
	v_cmp_gt_f32_e32 vcc, s42, v33
	s_nop 1
	v_cndmask_b32_e64 v63, 0, 32, vcc
	v_ldexp_f32 v33, v33, v63
	v_log_f32_e32 v33, v33
	s_nop 0
	v_mul_f32_e32 v63, 0x3f317217, v33
	v_fma_f32 v63, v33, s45, -v63
	v_fmac_f32_e32 v63, 0x3377d1cf, v33
	v_fmac_f32_e32 v63, 0x3f317217, v33
	v_cmp_lt_f32_e64 s[0:1], |v33|, s48
	s_nop 1
	v_cndmask_b32_e64 v33, v33, v63, s[0:1]
	v_cndmask_b32_e32 v63, 0, v222, vcc
	v_sub_f32_e32 v33, v33, v63
	v_sub_f32_e32 v33, v62, v33
	v_mul_f32_e32 v33, 0x3d800000, v33
	v_add_u32_e32 v62, 0x2800, v37
	ds_write2_b32 v62, v32, v33 offset1:96
	v_add_f32_e32 v32, v36, v34
	v_min_f32_e32 v33, 0, v32
	v_mul_f32_e64 v32, |v32|, s27
	v_exp_f32_e32 v32, v32
	s_nop 0
	v_add_f32_e32 v32, 1.0, v32
	v_cmp_gt_f32_e32 vcc, s42, v32
	s_nop 1
	v_cndmask_b32_e64 v34, 0, 32, vcc
	v_ldexp_f32 v32, v32, v34
	v_log_f32_e32 v32, v32
	s_nop 0
	v_mul_f32_e32 v34, 0x3f317217, v32
	v_fma_f32 v34, v32, s45, -v34
	v_fmac_f32_e32 v34, 0x3377d1cf, v32
	v_fmac_f32_e32 v34, 0x3f317217, v32
	v_cmp_lt_f32_e64 s[0:1], |v32|, s48
	s_nop 1
	v_cndmask_b32_e64 v32, v32, v34, s[0:1]
	v_cndmask_b32_e32 v34, 0, v222, vcc
	v_sub_f32_e32 v32, v32, v34
	v_sub_f32_e32 v32, v33, v32
	v_add_f32_e32 v33, v36, v35
	v_min_f32_e32 v34, 0, v33
	v_mul_f32_e64 v33, |v33|, s27
	v_exp_f32_e32 v33, v33
	v_mul_f32_e32 v32, 0x3d800000, v32
	v_add_f32_e32 v33, 1.0, v33
	v_cmp_gt_f32_e32 vcc, s42, v33
	s_nop 1
	v_cndmask_b32_e64 v35, 0, 32, vcc
	v_ldexp_f32 v33, v33, v35
	v_log_f32_e32 v33, v33
	s_nop 0
	v_mul_f32_e32 v35, 0x3f317217, v33
	v_fma_f32 v35, v33, s45, -v35
	v_fmac_f32_e32 v35, 0x3377d1cf, v33
	v_fmac_f32_e32 v35, 0x3f317217, v33
	v_cmp_lt_f32_e64 s[0:1], |v33|, s48
	s_nop 1
	v_cndmask_b32_e64 v33, v33, v35, s[0:1]
	s_add_i32 s0, s24, 8
	s_mul_hi_i32 s1, s0, 0x2aaaaaab
	s_lshr_b32 s25, s1, 31
	v_cndmask_b32_e32 v35, 0, v222, vcc
	s_add_i32 s1, s1, s25
	v_sub_f32_e32 v33, v33, v35
	s_mul_i32 s25, s1, -6
	v_sub_f32_e32 v33, v34, v33
	s_add_i32 s25, s25, s0
	v_mul_f32_e32 v33, 0x3d800000, v33
	v_add_u32_e32 v34, 0x2a00, v37
	s_lshl_b32 s41, s25, 6
	ds_write2_b32 v34, v32, v33 offset0:64 offset1:160
	v_add_u32_e32 v85, s41, v79
	v_lshl_add_u32 v32, s1, 10, v66
	ds_read2st64_b32 v[36:37], v85 offset0:16 offset1:22
	ds_read2_b32 v[62:63], v32 offset1:4
	ds_read2_b32 v[86:87], v32 offset0:8 offset1:12
	s_waitcnt lgkmcnt(1)
	v_mfma_f32_16x16x4_f32 v[32:35], v62, v36, 0
	s_add_i32 s24, s24, 16
	v_mfma_f32_16x16x4_f32 v[32:35], v63, v37, v[32:35]
	ds_read2st64_b32 v[36:37], v85 offset0:28 offset1:34
	s_waitcnt lgkmcnt(0)
	v_mfma_f32_16x16x4_f32 v[32:35], v86, v36, v[32:35]
	v_lshl_add_u32 v36, s25, 4, v2
	v_mfma_f32_16x16x4_f32 v[32:35], v87, v37, v[32:35]
	v_ashrrev_i32_e32 v37, 31, v36
	v_lshl_add_u64 v[36:37], v[36:37], 2, s[70:71]
	v_lshl_or_b32 v37, s1, 4, v65
	v_mul_lo_u32 v37, v37, s34
	v_add3_u32 v37, v67, s41, v37
	s_waitcnt vmcnt(10)
; __device__ __forceinline__ void gla_pre_items(LAS unsigned char* lds, const bf16* PROJ, const float* A2, const float* ba, unsigned char* GPRE, int first, int stride, int nitems) {
;     ...
;         for (int rep3 = 0; rep3 < 3; ++rep3) { const int id = wv + 8 * rep3, tt = id / 6, dd = id - tt * 6;
;             f32x4 z = (f32x4){0.f, 0.f, 0.f, 0.f};
; #pragma unroll
;             for (int ks = 0; ks < 4; ++ks) z = __builtin_amdgcn_mfma_f32_16x16x4f32(LRs[(16 * tt + c) * 16 + 4 * ks + g], A2s[(4 * ks + g) * 96 + 16 * dd + c], z, 0, 0, 0);
;             const float bb = ba[h * 96 + 16 * dd + c];
; #pragma unroll
;             for (int r = 0; r < 4; ++r) { const float zz = z[r] + bb; const float ls = fminf(zz, 0.f) - __logf(1.0f + __expf(-fabsf(zz)));
;                 Bs[(16 * tt + 4 * g + r) * 96 + 16 * dd + c] = ls * (1.0f / 16.0f); } }
	v_mov_b32_e32 v36, v189
	s_nop 2
	v_add_f32_e32 v32, v36, v32
	v_min_f32_e32 v62, 0, v32
	v_mul_f32_e64 v32, |v32|, s27
	v_exp_f32_e32 v32, v32
	v_add_f32_e32 v33, v36, v33
	v_add_f32_e32 v32, 1.0, v32
	v_cmp_gt_f32_e32 vcc, s42, v32
	s_nop 1
	v_cndmask_b32_e64 v63, 0, 32, vcc
	v_ldexp_f32 v32, v32, v63
	v_log_f32_e32 v32, v32
	s_nop 0
	v_mul_f32_e32 v63, 0x3f317217, v32
	v_fma_f32 v63, v32, s45, -v63
	v_fmac_f32_e32 v63, 0x3377d1cf, v32
	v_fmac_f32_e32 v63, 0x3f317217, v32
	v_cmp_lt_f32_e64 s[0:1], |v32|, s48
	s_nop 1
	v_cndmask_b32_e64 v32, v32, v63, s[0:1]
	v_cndmask_b32_e32 v63, 0, v222, vcc
	v_sub_f32_e32 v32, v32, v63
	v_sub_f32_e32 v32, v62, v32
	v_min_f32_e32 v62, 0, v33
	v_mul_f32_e64 v33, |v33|, s27
	v_exp_f32_e32 v33, v33
	v_mul_f32_e32 v32, 0x3d800000, v32
	v_add_f32_e32 v33, 1.0, v33
	v_cmp_gt_f32_e32 vcc, s42, v33
	s_nop 1
	v_cndmask_b32_e64 v63, 0, 32, vcc
	v_ldexp_f32 v33, v33, v63
	v_log_f32_e32 v33, v33
	s_nop 0
	v_mul_f32_e32 v63, 0x3f317217, v33
	v_fma_f32 v63, v33, s45, -v63
	v_fmac_f32_e32 v63, 0x3377d1cf, v33
	v_fmac_f32_e32 v63, 0x3f317217, v33
	v_cmp_lt_f32_e64 s[0:1], |v33|, s48
	s_nop 1
	v_cndmask_b32_e64 v33, v33, v63, s[0:1]
	v_cndmask_b32_e32 v63, 0, v222, vcc
	v_sub_f32_e32 v33, v33, v63
	v_sub_f32_e32 v33, v62, v33
	v_mul_f32_e32 v33, 0x3d800000, v33
	v_add_u32_e32 v62, 0x2800, v37
	ds_write2_b32 v62, v32, v33 offset1:96
	v_add_f32_e32 v32, v36, v34
	v_min_f32_e32 v33, 0, v32
	v_mul_f32_e64 v32, |v32|, s27
	v_exp_f32_e32 v32, v32
	s_nop 0
	v_add_f32_e32 v32, 1.0, v32
	v_cmp_gt_f32_e32 vcc, s42, v32
	s_nop 1
	v_cndmask_b32_e64 v34, 0, 32, vcc
	v_ldexp_f32 v32, v32, v34
	v_log_f32_e32 v32, v32
	s_nop 0
	v_mul_f32_e32 v34, 0x3f317217, v32
	v_fma_f32 v34, v32, s45, -v34
	v_fmac_f32_e32 v34, 0x3377d1cf, v32
	v_fmac_f32_e32 v34, 0x3f317217, v32
	v_cmp_lt_f32_e64 s[0:1], |v32|, s48
	s_nop 1
	v_cndmask_b32_e64 v32, v32, v34, s[0:1]
	v_cndmask_b32_e32 v34, 0, v222, vcc
	v_sub_f32_e32 v32, v32, v34
	v_sub_f32_e32 v32, v33, v32
	v_add_f32_e32 v33, v36, v35
	v_min_f32_e32 v34, 0, v33
	v_mul_f32_e64 v33, |v33|, s27
	v_exp_f32_e32 v33, v33
	v_mul_f32_e32 v32, 0x3d800000, v32
	v_add_f32_e32 v33, 1.0, v33
	v_cmp_gt_f32_e32 vcc, s42, v33
	s_nop 1
	v_cndmask_b32_e64 v35, 0, 32, vcc
	v_ldexp_f32 v33, v33, v35
	v_log_f32_e32 v33, v33
	s_nop 0
	v_mul_f32_e32 v35, 0x3f317217, v33
	v_fma_f32 v35, v33, s45, -v35
	v_fmac_f32_e32 v35, 0x3377d1cf, v33
	v_fmac_f32_e32 v35, 0x3f317217, v33
	v_cmp_lt_f32_e64 s[0:1], |v33|, s48
	s_nop 1
	v_cndmask_b32_e64 v33, v33, v35, s[0:1]
	s_mul_hi_i32 s0, s24, 0x2aaaaaab
	s_lshr_b32 s1, s0, 31
	v_cndmask_b32_e32 v35, 0, v222, vcc
	s_add_i32 s0, s0, s1
	v_sub_f32_e32 v33, v33, v35
	s_mul_i32 s1, s0, -6
	v_sub_f32_e32 v33, v34, v33
	s_add_i32 s1, s1, s24
	v_mul_f32_e32 v33, 0x3d800000, v33
	v_add_u32_e32 v34, 0x2a00, v37
	s_lshl_b32 s24, s1, 6
	ds_write2_b32 v34, v32, v33 offset0:64 offset1:160
	v_add_u32_e32 v85, s24, v79
	v_lshl_add_u32 v32, s0, 10, v66
	ds_read2st64_b32 v[36:37], v85 offset0:16 offset1:22
	ds_read2_b32 v[62:63], v32 offset1:4
	ds_read2_b32 v[86:87], v32 offset0:8 offset1:12
	s_waitcnt lgkmcnt(1)
	v_mfma_f32_16x16x4_f32 v[32:35], v62, v36, 0
	v_mfma_f32_16x16x4_f32 v[32:35], v63, v37, v[32:35]
	ds_read2st64_b32 v[36:37], v85 offset0:28 offset1:34
	s_waitcnt lgkmcnt(0)
	v_mfma_f32_16x16x4_f32 v[32:35], v86, v36, v[32:35]
	v_lshl_add_u32 v36, s1, 4, v2
	v_mfma_f32_16x16x4_f32 v[32:35], v87, v37, v[32:35]
	v_ashrrev_i32_e32 v37, 31, v36
	v_lshl_add_u64 v[36:37], v[36:37], 2, s[70:71]
	v_lshl_or_b32 v36, s0, 4, v65
	v_mul_lo_u32 v36, v36, s34
	v_add3_u32 v36, v67, s24, v36
	s_waitcnt vmcnt(9)
	v_mov_b32_e32 v2, v190
	s_nop 2
	v_add_f32_e32 v32, v2, v32
	v_min_f32_e32 v37, 0, v32
	v_mul_f32_e64 v32, |v32|, s27
	v_exp_f32_e32 v32, v32
	v_add_f32_e32 v33, v2, v33
	v_add_f32_e32 v32, 1.0, v32
	v_cmp_gt_f32_e32 vcc, s42, v32
	s_nop 1
	v_cndmask_b32_e64 v62, 0, 32, vcc
	v_ldexp_f32 v32, v32, v62
	v_log_f32_e32 v32, v32
	s_nop 0
	v_mul_f32_e32 v62, 0x3f317217, v32
	v_fma_f32 v62, v32, s45, -v62
	v_fmac_f32_e32 v62, 0x3377d1cf, v32
	v_fmac_f32_e32 v62, 0x3f317217, v32
	v_cmp_lt_f32_e64 s[0:1], |v32|, s48
	s_nop 1
	v_cndmask_b32_e64 v32, v32, v62, s[0:1]
	v_cndmask_b32_e32 v62, 0, v222, vcc
	v_sub_f32_e32 v32, v32, v62
	v_sub_f32_e32 v32, v37, v32
	v_min_f32_e32 v37, 0, v33
	v_mul_f32_e64 v33, |v33|, s27
	v_exp_f32_e32 v33, v33
	v_mul_f32_e32 v32, 0x3d800000, v32
	v_add_f32_e32 v33, 1.0, v33
	v_cmp_gt_f32_e32 vcc, s42, v33
	s_nop 1
	v_cndmask_b32_e64 v62, 0, 32, vcc
	v_ldexp_f32 v33, v33, v62
	v_log_f32_e32 v33, v33
	s_nop 0
	v_mul_f32_e32 v62, 0x3f317217, v33
	v_fma_f32 v62, v33, s45, -v62
	v_fmac_f32_e32 v62, 0x3377d1cf, v33
	v_fmac_f32_e32 v62, 0x3f317217, v33
	v_cmp_lt_f32_e64 s[0:1], |v33|, s48
	s_nop 1
	v_cndmask_b32_e64 v33, v33, v62, s[0:1]
	v_cndmask_b32_e32 v62, 0, v222, vcc
	v_sub_f32_e32 v33, v33, v62
	v_sub_f32_e32 v33, v37, v33
	v_mul_f32_e32 v33, 0x3d800000, v33
	v_add_u32_e32 v37, 0x2800, v36
	ds_write2_b32 v37, v32, v33 offset1:96
	v_add_f32_e32 v32, v2, v34
	v_min_f32_e32 v33, 0, v32
	v_mul_f32_e64 v32, |v32|, s27
	v_exp_f32_e32 v32, v32
	v_add_f32_e32 v2, v2, v35
	v_add_f32_e32 v32, 1.0, v32
	v_cmp_gt_f32_e32 vcc, s42, v32
	s_nop 1
	v_cndmask_b32_e64 v34, 0, 32, vcc
	v_ldexp_f32 v32, v32, v34
	v_log_f32_e32 v32, v32
	s_nop 0
	v_mul_f32_e32 v34, 0x3f317217, v32
	v_fma_f32 v34, v32, s45, -v34
	v_fmac_f32_e32 v34, 0x3377d1cf, v32
	v_fmac_f32_e32 v34, 0x3f317217, v32
	v_cmp_lt_f32_e64 s[0:1], |v32|, s48
	s_nop 1
	v_cndmask_b32_e64 v32, v32, v34, s[0:1]
	v_cndmask_b32_e32 v34, 0, v222, vcc
	v_sub_f32_e32 v32, v32, v34
	v_sub_f32_e32 v32, v33, v32
	v_min_f32_e32 v33, 0, v2
	v_mul_f32_e64 v2, |v2|, s27
	v_exp_f32_e32 v2, v2
	v_mul_f32_e32 v32, 0x3d800000, v32
	v_add_f32_e32 v2, 1.0, v2
	v_cmp_gt_f32_e32 vcc, s42, v2
	s_nop 1
	v_cndmask_b32_e64 v34, 0, 32, vcc
	v_ldexp_f32 v2, v2, v34
	v_log_f32_e32 v2, v2
	s_nop 0
	v_mul_f32_e32 v34, 0x3f317217, v2
	v_fma_f32 v34, v2, s45, -v34
	v_fmac_f32_e32 v34, 0x3377d1cf, v2
	v_fmac_f32_e32 v34, 0x3f317217, v2
	v_cmp_lt_f32_e64 s[0:1], |v2|, s48
	s_nop 1
	v_cndmask_b32_e64 v2, v2, v34, s[0:1]
	v_cndmask_b32_e32 v34, 0, v222, vcc
	v_sub_f32_e32 v2, v2, v34
	v_sub_f32_e32 v2, v33, v2
	v_mul_f32_e32 v2, 0x3d800000, v2
	v_add_u32_e32 v33, 0x2a00, v36
	ds_write2_b32 v33, v32, v2 offset0:64 offset1:160
	s_waitcnt lgkmcnt(0)
	s_barrier
; __device__ __forceinline__ void gla_pre_items(LAS unsigned char* lds, const bf16* PROJ, const float* A2, const float* ba, unsigned char* GPRE, int first, int stride, int nitems) {
;     ...
;     if (tid < 96) { float gv[64];
; #pragma unroll
;         for (int t = 0; t < 64; ++t) gv[t] = Bs[t * 96 + tid];
;         float run = 0.f;
; #pragma unroll
;         for (int t = 0; t < 64; ++t) { run += gv[t]; Bs[t * 96 + tid] = run; } }
	s_and_saveexec_b64 s[0:1], s[16:17]
	s_cbranch_execz .LBB0_678
	v_add_u32_e32 v2, 0x2800, v68
	ds_read2_b32 v[32:33], v2 offset1:96
	v_add_u32_e32 v85, 0x2a00, v68
	ds_read2_b32 v[34:35], v85 offset0:64 offset1:160
	v_add_u32_e32 v142, 0x2c00, v68
	ds_read2_b32 v[36:37], v142 offset0:128 offset1:224
	v_add_u32_e32 v143, 0x3000, v68
	s_waitcnt lgkmcnt(2)
	v_add_f32_e32 v32, 0, v32
	ds_read2_b32 v[62:63], v143 offset0:64 offset1:160
	v_add_f32_e32 v33, v32, v33
	v_add_u32_e32 v144, 0x3400, v68
	ds_write2_b32 v2, v32, v33 offset1:96
	s_waitcnt lgkmcnt(3)
	v_add_f32_e32 v2, v33, v34
	ds_read2_b32 v[86:87], v144 offset1:96
	v_add_f32_e32 v32, v2, v35
	v_add_u32_e32 v145, 0x3600, v68
	ds_write2_b32 v85, v2, v32 offset0:64 offset1:160
	s_waitcnt lgkmcnt(4)
	v_add_f32_e32 v2, v32, v36
	ds_read2_b32 v[88:89], v145 offset0:64 offset1:160
	v_add_f32_e32 v32, v2, v37
	v_add_u32_e32 v146, 0x3800, v68
	ds_write2_b32 v142, v2, v32 offset0:128 offset1:224
	s_waitcnt lgkmcnt(5)
	v_add_f32_e32 v2, v32, v62
	ds_read2_b32 v[90:91], v146 offset0:128 offset1:224
	v_add_f32_e32 v32, v2, v63
	v_add_u32_e32 v147, 0x3c00, v68
	ds_write2_b32 v143, v2, v32 offset0:64 offset1:160
	s_waitcnt lgkmcnt(5)
	v_add_f32_e32 v2, v32, v86
	ds_read2_b32 v[92:93], v147 offset0:64 offset1:160
	v_add_f32_e32 v32, v2, v87
	v_add_u32_e32 v148, 0x4000, v68
	ds_write2_b32 v144, v2, v32 offset1:96
	s_waitcnt lgkmcnt(5)
	v_add_f32_e32 v2, v32, v88
	ds_read2_b32 v[94:95], v148 offset1:96
	v_add_f32_e32 v32, v2, v89
	v_add_u32_e32 v149, 0x4200, v68
	ds_write2_b32 v145, v2, v32 offset0:64 offset1:160
	s_waitcnt lgkmcnt(5)
	v_add_f32_e32 v2, v32, v90
	ds_read2_b32 v[96:97], v149 offset0:64 offset1:160
	v_add_f32_e32 v32, v2, v91
	v_add_u32_e32 v150, 0x4400, v68
	ds_write2_b32 v146, v2, v32 offset0:128 offset1:224
	s_waitcnt lgkmcnt(5)
	v_add_f32_e32 v2, v32, v92
	ds_read2_b32 v[98:99], v150 offset0:128 offset1:224
	v_add_f32_e32 v32, v2, v93
	v_add_u32_e32 v151, 0x4800, v68
	ds_write2_b32 v147, v2, v32 offset0:64 offset1:160
	s_waitcnt lgkmcnt(5)
	v_add_f32_e32 v2, v32, v94
	ds_read2_b32 v[100:101], v151 offset0:64 offset1:160
	v_add_f32_e32 v32, v2, v95
	v_add_u32_e32 v152, 0x4c00, v68
	ds_write2_b32 v148, v2, v32 offset1:96
	s_waitcnt lgkmcnt(5)
	v_add_f32_e32 v2, v32, v96
	ds_read2_b32 v[102:103], v152 offset1:96
	v_add_f32_e32 v32, v2, v97
	v_add_u32_e32 v153, 0x4e00, v68
	ds_write2_b32 v149, v2, v32 offset0:64 offset1:160
	s_waitcnt lgkmcnt(5)
	v_add_f32_e32 v2, v32, v98
	ds_read2_b32 v[104:105], v153 offset0:64 offset1:160
	v_add_f32_e32 v32, v2, v99
	v_add_u32_e32 v154, 0x5000, v68
	ds_write2_b32 v150, v2, v32 offset0:128 offset1:224
	s_waitcnt lgkmcnt(5)
	v_add_f32_e32 v2, v32, v100
	ds_read2_b32 v[106:107], v154 offset0:128 offset1:224
	v_add_f32_e32 v32, v2, v101
	v_add_u32_e32 v155, 0x5400, v68
	ds_write2_b32 v151, v2, v32 offset0:64 offset1:160
	s_waitcnt lgkmcnt(5)
	v_add_f32_e32 v2, v32, v102
	ds_read2_b32 v[108:109], v155 offset0:64 offset1:160
	v_add_f32_e32 v32, v2, v103
	v_add_u32_e32 v156, 0x5800, v68
	ds_write2_b32 v152, v2, v32 offset1:96
	s_waitcnt lgkmcnt(5)
	v_add_f32_e32 v2, v32, v104
	ds_read2_b32 v[110:111], v156 offset1:96
	v_add_f32_e32 v32, v2, v105
	v_add_u32_e32 v157, 0x5a00, v68
	ds_write2_b32 v153, v2, v32 offset0:64 offset1:160
	s_waitcnt lgkmcnt(5)
	v_add_f32_e32 v2, v32, v106
	ds_read2_b32 v[112:113], v157 offset0:64 offset1:160
	v_add_f32_e32 v32, v2, v107
	v_add_u32_e32 v158, 0x5c00, v68
	ds_write2_b32 v154, v2, v32 offset0:128 offset1:224
	s_waitcnt lgkmcnt(5)
	v_add_f32_e32 v2, v32, v108
	ds_read2_b32 v[114:115], v158 offset0:128 offset1:224
	v_add_f32_e32 v32, v2, v109
	v_add_u32_e32 v159, 0x6000, v68
	ds_write2_b32 v155, v2, v32 offset0:64 offset1:160
	s_waitcnt lgkmcnt(5)
	v_add_f32_e32 v2, v32, v110
	ds_read2_b32 v[116:117], v159 offset0:64 offset1:160
	v_add_f32_e32 v32, v2, v111
	v_add_u32_e32 v160, 0x6400, v68
	ds_write2_b32 v156, v2, v32 offset1:96
	s_waitcnt lgkmcnt(5)
	v_add_f32_e32 v2, v32, v112
	ds_read2_b32 v[118:119], v160 offset1:96
	v_add_f32_e32 v32, v2, v113
	v_add_u32_e32 v161, 0x6600, v68
	ds_write2_b32 v157, v2, v32 offset0:64 offset1:160
	s_waitcnt lgkmcnt(5)
	v_add_f32_e32 v2, v32, v114
	ds_read2_b32 v[120:121], v161 offset0:64 offset1:160
	v_add_f32_e32 v32, v2, v115
	v_add_u32_e32 v162, 0x6800, v68
	ds_write2_b32 v158, v2, v32 offset0:128 offset1:224
	s_waitcnt lgkmcnt(5)
	v_add_f32_e32 v2, v32, v116
	ds_read2_b32 v[122:123], v162 offset0:128 offset1:224
	v_add_f32_e32 v32, v2, v117
	v_add_u32_e32 v163, 0x6c00, v68
	ds_write2_b32 v159, v2, v32 offset0:64 offset1:160
	s_waitcnt lgkmcnt(5)
	v_add_f32_e32 v2, v32, v118
	ds_read2_b32 v[124:125], v163 offset0:64 offset1:160
	v_add_f32_e32 v32, v2, v119
	v_add_u32_e32 v164, 0x7000, v68
	ds_write2_b32 v160, v2, v32 offset1:96
	s_waitcnt lgkmcnt(5)
	v_add_f32_e32 v2, v32, v120
	ds_read2_b32 v[126:127], v164 offset1:96
	v_add_f32_e32 v32, v2, v121
	v_add_u32_e32 v165, 0x7200, v68
	ds_write2_b32 v161, v2, v32 offset0:64 offset1:160
	s_waitcnt lgkmcnt(5)
	v_add_f32_e32 v2, v32, v122
	ds_read2_b32 v[128:129], v165 offset0:64 offset1:160
	v_add_f32_e32 v32, v2, v123
	v_add_u32_e32 v166, 0x7400, v68
	ds_write2_b32 v162, v2, v32 offset0:128 offset1:224
	s_waitcnt lgkmcnt(5)
	v_add_f32_e32 v2, v32, v124
	ds_read2_b32 v[130:131], v166 offset0:128 offset1:224
	v_add_f32_e32 v32, v2, v125
	v_add_u32_e32 v167, 0x7800, v68
	ds_write2_b32 v163, v2, v32 offset0:64 offset1:160
	s_waitcnt lgkmcnt(5)
	v_add_f32_e32 v2, v32, v126
	ds_read2_b32 v[132:133], v167 offset0:64 offset1:160
	v_add_f32_e32 v32, v2, v127
	v_add_u32_e32 v168, 0x7c00, v68
	ds_write2_b32 v164, v2, v32 offset1:96
	s_waitcnt lgkmcnt(5)
	v_add_f32_e32 v2, v32, v128
	ds_read2_b32 v[134:135], v168 offset1:96
	v_add_f32_e32 v32, v2, v129
	v_add_u32_e32 v169, 0x7e00, v68
	ds_write2_b32 v165, v2, v32 offset0:64 offset1:160
	s_waitcnt lgkmcnt(5)
	v_add_f32_e32 v2, v32, v130
	ds_read2_b32 v[136:137], v169 offset0:64 offset1:160
	v_add_f32_e32 v32, v2, v131
	v_add_u32_e32 v170, 0x8000, v68
	ds_write2_b32 v166, v2, v32 offset0:128 offset1:224
	s_waitcnt lgkmcnt(5)
	v_add_f32_e32 v2, v32, v132
	ds_read2_b32 v[138:139], v170 offset0:128 offset1:224
	v_add_f32_e32 v32, v2, v133
	v_add_u32_e32 v171, 0x8400, v68
	ds_write2_b32 v167, v2, v32 offset0:64 offset1:160
	s_waitcnt lgkmcnt(5)
	v_add_f32_e32 v2, v32, v134
	ds_read2_b32 v[140:141], v171 offset0:64 offset1:160
	v_add_f32_e32 v32, v2, v135
	ds_write2_b32 v168, v2, v32 offset1:96
	s_waitcnt lgkmcnt(5)
	v_add_f32_e32 v2, v32, v136
	v_add_f32_e32 v32, v2, v137
	ds_write2_b32 v169, v2, v32 offset0:64 offset1:160
	s_waitcnt lgkmcnt(4)
	v_add_f32_e32 v2, v32, v138
	v_add_f32_e32 v32, v2, v139
	ds_write2_b32 v170, v2, v32 offset0:128 offset1:224
	s_waitcnt lgkmcnt(3)
	v_add_f32_e32 v2, v32, v140
	v_add_f32_e32 v32, v2, v141
	ds_write2_b32 v171, v2, v32 offset0:64 offset1:160

; __device__ __forceinline__ void gla_pre_items(LAS unsigned char* lds, const bf16* PROJ, const float* A2, const float* ba, unsigned char* GPRE, int first, int stride, int nitems) {
;     ...
;     const int bh = item >> 5, ch = item & 31, b = bh >> 2, h = bh & 3;
;     unsigned char* gp = GPRE + (size_t)item * GP_ITEM;
;     ...
;     if (tid < 96) ((float*)(gp + GP_DEC))[tid] = __expf(Bs[63 * 96 + tid]);
;     __syncthreads();
.LBB0_681:
	s_waitcnt vmcnt(0)
	s_or_b64 exec, exec, s[0:1]
	s_mul_i32 s0, s40, 0xe200
	v_readlane_b32 s24, v255, 30
	s_mul_hi_i32 s1, s40, 0xe200
	s_add_u32 s0, s24, s0
	v_readlane_b32 s24, v255, 31
	s_addc_u32 s1, s24, s1
	s_and_saveexec_b64 s[24:25], s[16:17]
	s_cbranch_execz .LBB0_683
	ds_read_b32 v2, v68 offset:34432
	v_lshl_add_u64 v[32:33], v[38:39], 2, s[0:1]
	v_add_co_u32_e32 v32, vcc, 0xe000, v32
	s_waitcnt lgkmcnt(0)
	v_mul_f32_e32 v2, 0x3fb8aa3b, v2
	v_exp_f32_e32 v2, v2
	v_addc_co_u32_e32 v33, vcc, 0, v33, vcc
	global_store_dword v[32:33], v2, off

; #define LAS __attribute__((address_space(3)))
; __device__ __forceinline__ void gla_pre_items(LAS unsigned char* lds, const bf16* PROJ, const float* A2, const float* ba, unsigned char* GPRE, int first, int stride, int nitems) {
;     ...
; #pragma unroll
;     for (int i = 0; i < 3; ++i) { const int idx = tid + 512 * i, t = idx / 24, cq = idx - t * 24;
;         if (cq < 12) *(LAS v4u*)(QTs + t * 104 + cq * 8) = rqk[i]; else *(LAS v4u*)(KTs + t * 104 + (cq - 12) * 8) = rqk[i];
;         A2s[idx] = ra2[i];
.LBB0_696:
	v_add_u32_e32 v2, v69, v70
	ds_write_b128 v2, v[8:11] offset:47936
	s_andn2_saveexec_b64 s[0:1], s[0:1]
	s_cbranch_execnz .LBB0_663
	s_branch .LBB0_664
